# residual GEMM epilogues (A_OUT/B_OUT/FFN-out): base rows requested 16-32 at a time instead of a load-wait-fma-store ladder
# speedup vs baseline: 1.0093x; 1.0093x over previous
.LBB0_732:
	v_lshl_add_u32 v152, s1, 8, v142
	v_lshl_or_b32 v154, s0, 8, v144
	v_ashrrev_i32_e32 v153, 31, v152
	v_ashrrev_i32_e32 v155, 31, v154
	v_lshl_add_u32 v252, v152, 10, v154
	v_lshlrev_b32_e32 v252, 2, v252
	v_mov_b32_e32 v236, v252
	v_add_u32_e32 v237, 0x10000, v252
	v_add_u32_e32 v238, 0x20000, v252
	v_add_u32_e32 v239, 0x30000, v252
	v_lshl_add_u32 v240, s12, 0, v252
	v_lshl_add_u32 v241, s14, 0, v252
	v_lshl_add_u32 v242, s18, 0, v252
	v_lshl_add_u32 v243, s20, 0, v252
	s_andn2_b64 vcc, exec, s[2:3]
	s_mov_b64 s[2:3], -1
	global_load_dwordx4 v[168:171], v236, s[52:53]
	global_load_dwordx4 v[172:175], v236, s[52:53] offset:64
	global_load_dwordx4 v[176:179], v236, s[52:53] offset:512
	global_load_dwordx4 v[180:183], v236, s[52:53] offset:576
	global_load_dwordx4 v[184:187], v237, s[52:53]
	global_load_dwordx4 v[188:191], v237, s[52:53] offset:64
	global_load_dwordx4 v[192:195], v237, s[52:53] offset:512
	global_load_dwordx4 v[196:199], v237, s[52:53] offset:576
	global_load_dwordx4 v[204:207], v238, s[52:53]
	global_load_dwordx4 v[208:211], v238, s[52:53] offset:64
	global_load_dwordx4 v[212:215], v238, s[52:53] offset:512
	global_load_dwordx4 v[216:219], v238, s[52:53] offset:576
	global_load_dwordx4 v[220:223], v239, s[52:53]
	global_load_dwordx4 v[224:227], v239, s[52:53] offset:64
	global_load_dwordx4 v[228:231], v239, s[52:53] offset:512
	global_load_dwordx4 v[232:235], v239, s[52:53] offset:576
	s_waitcnt vmcnt(15)
	v_fma_f32 v124, v168, s10, v124
	v_fma_f32 v125, v169, s10, v125
	v_fma_f32 v126, v170, s10, v126
	v_fma_f32 v127, v171, s10, v127
	global_store_dwordx4 v236, v[124:127], s[24:25]
	global_load_dwordx4 v[168:171], v240, s[52:53]
	s_waitcnt vmcnt(16)
	v_fma_f32 v120, v172, s10, v120
	v_fma_f32 v121, v173, s10, v121
	v_fma_f32 v122, v174, s10, v122
	v_fma_f32 v123, v175, s10, v123
	global_store_dwordx4 v236, v[120:123], s[24:25] offset:64
	global_load_dwordx4 v[172:175], v240, s[52:53] offset:64
	s_waitcnt vmcnt(17)
	v_fma_f32 v116, v176, s10, v116
	v_fma_f32 v117, v177, s10, v117
	v_fma_f32 v118, v178, s10, v118
	v_fma_f32 v119, v179, s10, v119
	global_store_dwordx4 v236, v[116:119], s[24:25] offset:512
	global_load_dwordx4 v[176:179], v240, s[52:53] offset:512
	s_waitcnt vmcnt(18)
	v_fma_f32 v104, v180, s10, v104
	v_fma_f32 v105, v181, s10, v105
	v_fma_f32 v106, v182, s10, v106
	v_fma_f32 v107, v183, s10, v107
	global_store_dwordx4 v236, v[104:107], s[24:25] offset:576
	global_load_dwordx4 v[180:183], v240, s[52:53] offset:576
	s_waitcnt vmcnt(19)
	v_fma_f32 v112, v184, s10, v112
	v_fma_f32 v113, v185, s10, v113
	v_fma_f32 v114, v186, s10, v114
	v_fma_f32 v115, v187, s10, v115
	global_store_dwordx4 v237, v[112:115], s[24:25]
	global_load_dwordx4 v[184:187], v241, s[52:53]
	s_waitcnt vmcnt(20)
	v_fma_f32 v108, v188, s10, v108
	v_fma_f32 v109, v189, s10, v109
	v_fma_f32 v110, v190, s10, v110
	v_fma_f32 v111, v191, s10, v111
	global_store_dwordx4 v237, v[108:111], s[24:25] offset:64
	global_load_dwordx4 v[188:191], v241, s[52:53] offset:64
	s_waitcnt vmcnt(21)
	v_fma_f32 v100, v192, s10, v100
	v_fma_f32 v101, v193, s10, v101
	v_fma_f32 v102, v194, s10, v102
	v_fma_f32 v103, v195, s10, v103
	global_store_dwordx4 v237, v[100:103], s[24:25] offset:512
	global_load_dwordx4 v[192:195], v241, s[52:53] offset:512
	s_waitcnt vmcnt(22)
	v_fma_f32 v88, v196, s10, v88
	v_fma_f32 v89, v197, s10, v89
	v_fma_f32 v90, v198, s10, v90
	v_fma_f32 v91, v199, s10, v91
	global_store_dwordx4 v237, v[88:91], s[24:25] offset:576
	global_load_dwordx4 v[196:199], v241, s[52:53] offset:576
	s_waitcnt vmcnt(23)
	v_fma_f32 v96, v204, s10, v96
	v_fma_f32 v97, v205, s10, v97
	v_fma_f32 v98, v206, s10, v98
	v_fma_f32 v99, v207, s10, v99
	global_store_dwordx4 v238, v[96:99], s[24:25]
	global_load_dwordx4 v[204:207], v242, s[52:53]
	s_waitcnt vmcnt(24)
	v_fma_f32 v92, v208, s10, v92
	v_fma_f32 v93, v209, s10, v93
	v_fma_f32 v94, v210, s10, v94
	v_fma_f32 v95, v211, s10, v95
	global_store_dwordx4 v238, v[92:95], s[24:25] offset:64
	global_load_dwordx4 v[208:211], v242, s[52:53] offset:64
	s_waitcnt vmcnt(25)
	v_fma_f32 v84, v212, s10, v84
	v_fma_f32 v85, v213, s10, v85
	v_fma_f32 v86, v214, s10, v86
	v_fma_f32 v87, v215, s10, v87
	global_store_dwordx4 v238, v[84:87], s[24:25] offset:512
	global_load_dwordx4 v[212:215], v242, s[52:53] offset:512
	s_waitcnt vmcnt(26)
	v_fma_f32 v72, v216, s10, v72
	v_fma_f32 v73, v217, s10, v73
	v_fma_f32 v74, v218, s10, v74
	v_fma_f32 v75, v219, s10, v75
	global_store_dwordx4 v238, v[72:75], s[24:25] offset:576
	global_load_dwordx4 v[216:219], v242, s[52:53] offset:576
	s_waitcnt vmcnt(27)
	v_fma_f32 v80, v220, s10, v80
	v_fma_f32 v81, v221, s10, v81
	v_fma_f32 v82, v222, s10, v82
	v_fma_f32 v83, v223, s10, v83
	global_store_dwordx4 v239, v[80:83], s[24:25]
	global_load_dwordx4 v[220:223], v243, s[52:53]
	s_waitcnt vmcnt(28)
	v_fma_f32 v76, v224, s10, v76
	v_fma_f32 v77, v225, s10, v77
	v_fma_f32 v78, v226, s10, v78
	v_fma_f32 v79, v227, s10, v79
	global_store_dwordx4 v239, v[76:79], s[24:25] offset:64
	global_load_dwordx4 v[224:227], v243, s[52:53] offset:64
	s_waitcnt vmcnt(29)
	v_fma_f32 v68, v228, s10, v68
	v_fma_f32 v69, v229, s10, v69
	v_fma_f32 v70, v230, s10, v70
	v_fma_f32 v71, v231, s10, v71
	global_store_dwordx4 v239, v[68:71], s[24:25] offset:512
	global_load_dwordx4 v[228:231], v243, s[52:53] offset:512
	s_waitcnt vmcnt(30)
	v_fma_f32 v64, v232, s10, v64
	v_fma_f32 v65, v233, s10, v65
	v_fma_f32 v66, v234, s10, v66
	v_fma_f32 v67, v235, s10, v67
	global_store_dwordx4 v239, v[64:67], s[24:25] offset:576
	global_load_dwordx4 v[232:235], v243, s[52:53] offset:576
	s_waitcnt vmcnt(30)
	v_fma_f32 v60, v168, s10, v60
	v_fma_f32 v61, v169, s10, v61
	v_fma_f32 v62, v170, s10, v62
	v_fma_f32 v63, v171, s10, v63
	global_store_dwordx4 v240, v[60:63], s[24:25]
	s_waitcnt vmcnt(29)
	v_fma_f32 v56, v172, s10, v56
	v_fma_f32 v57, v173, s10, v57
	v_fma_f32 v58, v174, s10, v58
	v_fma_f32 v59, v175, s10, v59
	global_store_dwordx4 v240, v[56:59], s[24:25] offset:64
	s_waitcnt vmcnt(28)
	v_fma_f32 v52, v176, s10, v52
	v_fma_f32 v53, v177, s10, v53
	v_fma_f32 v54, v178, s10, v54
	v_fma_f32 v55, v179, s10, v55
	global_store_dwordx4 v240, v[52:55], s[24:25] offset:512
	s_waitcnt vmcnt(27)
	v_fma_f32 v40, v180, s10, v40
	v_fma_f32 v41, v181, s10, v41
	v_fma_f32 v42, v182, s10, v42
	v_fma_f32 v43, v183, s10, v43
	global_store_dwordx4 v240, v[40:43], s[24:25] offset:576
	s_waitcnt vmcnt(26)
	v_fma_f32 v48, v184, s10, v48
	v_fma_f32 v49, v185, s10, v49
	v_fma_f32 v50, v186, s10, v50
	v_fma_f32 v51, v187, s10, v51
	global_store_dwordx4 v241, v[48:51], s[24:25]
	s_waitcnt vmcnt(25)
	v_fma_f32 v44, v188, s10, v44
	v_fma_f32 v45, v189, s10, v45
	v_fma_f32 v46, v190, s10, v46
	v_fma_f32 v47, v191, s10, v47
	global_store_dwordx4 v241, v[44:47], s[24:25] offset:64
	s_waitcnt vmcnt(24)
	v_fma_f32 v36, v192, s10, v36
	v_fma_f32 v37, v193, s10, v37
	v_fma_f32 v38, v194, s10, v38
	v_fma_f32 v39, v195, s10, v39
	global_store_dwordx4 v241, v[36:39], s[24:25] offset:512
	s_waitcnt vmcnt(23)
	v_fma_f32 v24, v196, s10, v24
	v_fma_f32 v25, v197, s10, v25
	v_fma_f32 v26, v198, s10, v26
	v_fma_f32 v27, v199, s10, v27
	global_store_dwordx4 v241, v[24:27], s[24:25] offset:576
	s_waitcnt vmcnt(22)
	v_fma_f32 v32, v204, s10, v32
	v_fma_f32 v33, v205, s10, v33
	v_fma_f32 v34, v206, s10, v34
	v_fma_f32 v35, v207, s10, v35
	global_store_dwordx4 v242, v[32:35], s[24:25]
	s_waitcnt vmcnt(21)
	v_fma_f32 v28, v208, s10, v28
	v_fma_f32 v29, v209, s10, v29
	v_fma_f32 v30, v210, s10, v30
	v_fma_f32 v31, v211, s10, v31
	global_store_dwordx4 v242, v[28:31], s[24:25] offset:64
	s_waitcnt vmcnt(20)
	v_fma_f32 v20, v212, s10, v20
	v_fma_f32 v21, v213, s10, v21
	v_fma_f32 v22, v214, s10, v22
	v_fma_f32 v23, v215, s10, v23
	global_store_dwordx4 v242, v[20:23], s[24:25] offset:512
	s_waitcnt vmcnt(19)
	v_fma_f32 v8, v216, s10, v8
	v_fma_f32 v9, v217, s10, v9
	v_fma_f32 v10, v218, s10, v10
	v_fma_f32 v11, v219, s10, v11
	global_store_dwordx4 v242, v[8:11], s[24:25] offset:576
	s_waitcnt vmcnt(18)
	v_fma_f32 v16, v220, s10, v16
	v_fma_f32 v17, v221, s10, v17
	v_fma_f32 v18, v222, s10, v18
	v_fma_f32 v19, v223, s10, v19
	global_store_dwordx4 v243, v[16:19], s[24:25]
	s_waitcnt vmcnt(17)
	v_fma_f32 v12, v224, s10, v12
	v_fma_f32 v13, v225, s10, v13
	v_fma_f32 v14, v226, s10, v14
	v_fma_f32 v15, v227, s10, v15
	global_store_dwordx4 v243, v[12:15], s[24:25] offset:64
	s_waitcnt vmcnt(16)
	v_fma_f32 v4, v228, s10, v4
	v_fma_f32 v5, v229, s10, v5
	v_fma_f32 v6, v230, s10, v6
	v_fma_f32 v7, v231, s10, v7
	global_store_dwordx4 v243, v[4:7], s[24:25] offset:512
	s_waitcnt vmcnt(15)
	v_fma_f32 v0, v232, s10, v0
	v_fma_f32 v1, v233, s10, v1
	v_fma_f32 v2, v234, s10, v2
	v_fma_f32 v3, v235, s10, v3
	global_store_dwordx4 v243, v[0:3], s[24:25] offset:576
	s_cbranch_vccnz .LBB0_725
	s_andn2_b64 vcc, exec, s[4:5]
	s_cbranch_vccnz .LBB0_724
	s_barrier
	s_branch .LBB0_724

.LBB0_1021:
	v_lshl_add_u32 v144, s1, 8, v146
	v_lshl_or_b32 v142, s0, 8, v148
	v_ashrrev_i32_e32 v145, 31, v144
	v_ashrrev_i32_e32 v143, 31, v142
	v_lshl_add_u32 v252, v144, 10, v142
	v_lshlrev_b32_e32 v252, 2, v252
	v_mov_b32_e32 v236, v252
	v_lshrrev_b32_e32 v244, 1, v236
	v_add_u32_e32 v237, 0x10000, v252
	v_lshrrev_b32_e32 v245, 1, v237
	v_add_u32_e32 v238, 0x20000, v252
	v_lshrrev_b32_e32 v246, 1, v238
	v_add_u32_e32 v239, 0x30000, v252
	v_lshrrev_b32_e32 v247, 1, v239
	v_lshl_add_u32 v240, s18, 2, v252
	v_lshrrev_b32_e32 v248, 1, v240
	v_lshl_add_u32 v241, s20, 2, v252
	v_lshrrev_b32_e32 v249, 1, v241
	v_lshl_add_u32 v242, s34, 2, v252
	v_lshrrev_b32_e32 v250, 1, v242
	v_lshl_add_u32 v243, s44, 2, v252
	v_lshrrev_b32_e32 v251, 1, v243
	s_and_b64 vcc, exec, s[2:3]
	s_mov_b64 s[2:3], -1
	global_load_dwordx2 v[168:169], v244, s[8:9]
	global_load_dwordx2 v[170:171], v244, s[8:9] offset:32
	global_load_dwordx2 v[172:173], v244, s[8:9] offset:256
	global_load_dwordx2 v[174:175], v244, s[8:9] offset:288
	global_load_dwordx2 v[176:177], v245, s[8:9]
	global_load_dwordx2 v[178:179], v245, s[8:9] offset:32
	global_load_dwordx2 v[180:181], v245, s[8:9] offset:256
	global_load_dwordx2 v[182:183], v245, s[8:9] offset:288
	global_load_dwordx2 v[184:185], v246, s[8:9]
	global_load_dwordx2 v[186:187], v246, s[8:9] offset:32
	global_load_dwordx2 v[188:189], v246, s[8:9] offset:256
	global_load_dwordx2 v[190:191], v246, s[8:9] offset:288
	global_load_dwordx2 v[192:193], v247, s[8:9]
	global_load_dwordx2 v[194:195], v247, s[8:9] offset:32
	global_load_dwordx2 v[196:197], v247, s[8:9] offset:256
	global_load_dwordx2 v[198:199], v247, s[8:9] offset:288
	global_load_dwordx2 v[204:205], v248, s[8:9]
	global_load_dwordx2 v[206:207], v248, s[8:9] offset:32
	global_load_dwordx2 v[208:209], v248, s[8:9] offset:256
	global_load_dwordx2 v[210:211], v248, s[8:9] offset:288
	global_load_dwordx2 v[212:213], v249, s[8:9]
	global_load_dwordx2 v[214:215], v249, s[8:9] offset:32
	global_load_dwordx2 v[216:217], v249, s[8:9] offset:256
	global_load_dwordx2 v[218:219], v249, s[8:9] offset:288
	global_load_dwordx2 v[220:221], v250, s[8:9]
	global_load_dwordx2 v[222:223], v250, s[8:9] offset:32
	global_load_dwordx2 v[224:225], v250, s[8:9] offset:256
	global_load_dwordx2 v[226:227], v250, s[8:9] offset:288
	global_load_dwordx2 v[228:229], v251, s[8:9]
	global_load_dwordx2 v[230:231], v251, s[8:9] offset:32
	global_load_dwordx2 v[232:233], v251, s[8:9] offset:256
	global_load_dwordx2 v[234:235], v251, s[8:9] offset:288
	s_waitcnt vmcnt(31)
	v_lshlrev_b32_e32 v252, 16, v168
	v_and_b32_e32 v168, 0xffff0000, v168
	v_lshlrev_b32_e32 v253, 16, v169
	v_and_b32_e32 v169, 0xffff0000, v169
	v_fma_f32 v124, v252, s14, v124
	v_fma_f32 v125, v168, s14, v125
	v_fma_f32 v126, v253, s14, v126
	v_fma_f32 v127, v169, s14, v127
	global_store_dwordx4 v236, v[124:127], s[24:25]
	s_waitcnt vmcnt(31)
	v_lshlrev_b32_e32 v252, 16, v170
	v_and_b32_e32 v170, 0xffff0000, v170
	v_lshlrev_b32_e32 v253, 16, v171
	v_and_b32_e32 v171, 0xffff0000, v171
	v_fma_f32 v120, v252, s14, v120
	v_fma_f32 v121, v170, s14, v121
	v_fma_f32 v122, v253, s14, v122
	v_fma_f32 v123, v171, s14, v123
	global_store_dwordx4 v236, v[120:123], s[24:25] offset:64
	s_waitcnt vmcnt(31)
	v_lshlrev_b32_e32 v252, 16, v172
	v_and_b32_e32 v172, 0xffff0000, v172
	v_lshlrev_b32_e32 v253, 16, v173
	v_and_b32_e32 v173, 0xffff0000, v173
	v_fma_f32 v116, v252, s14, v116
	v_fma_f32 v117, v172, s14, v117
	v_fma_f32 v118, v253, s14, v118
	v_fma_f32 v119, v173, s14, v119
	global_store_dwordx4 v236, v[116:119], s[24:25] offset:512
	s_waitcnt vmcnt(31)
	v_lshlrev_b32_e32 v252, 16, v174
	v_and_b32_e32 v174, 0xffff0000, v174
	v_lshlrev_b32_e32 v253, 16, v175
	v_and_b32_e32 v175, 0xffff0000, v175
	v_fma_f32 v108, v252, s14, v108
	v_fma_f32 v109, v174, s14, v109
	v_fma_f32 v110, v253, s14, v110
	v_fma_f32 v111, v175, s14, v111
	global_store_dwordx4 v236, v[108:111], s[24:25] offset:576
	s_waitcnt vmcnt(31)
	v_lshlrev_b32_e32 v252, 16, v176
	v_and_b32_e32 v176, 0xffff0000, v176
	v_lshlrev_b32_e32 v253, 16, v177
	v_and_b32_e32 v177, 0xffff0000, v177
	v_fma_f32 v112, v252, s14, v112
	v_fma_f32 v113, v176, s14, v113
	v_fma_f32 v114, v253, s14, v114
	v_fma_f32 v115, v177, s14, v115
	global_store_dwordx4 v237, v[112:115], s[24:25]
	s_waitcnt vmcnt(31)
	v_lshlrev_b32_e32 v252, 16, v178
	v_and_b32_e32 v178, 0xffff0000, v178
	v_lshlrev_b32_e32 v253, 16, v179
	v_and_b32_e32 v179, 0xffff0000, v179
	v_fma_f32 v104, v252, s14, v104
	v_fma_f32 v105, v178, s14, v105
	v_fma_f32 v106, v253, s14, v106
	v_fma_f32 v107, v179, s14, v107
	global_store_dwordx4 v237, v[104:107], s[24:25] offset:64
	s_waitcnt vmcnt(31)
	v_lshlrev_b32_e32 v252, 16, v180
	v_and_b32_e32 v180, 0xffff0000, v180
	v_lshlrev_b32_e32 v253, 16, v181
	v_and_b32_e32 v181, 0xffff0000, v181
	v_fma_f32 v100, v252, s14, v100
	v_fma_f32 v101, v180, s14, v101
	v_fma_f32 v102, v253, s14, v102
	v_fma_f32 v103, v181, s14, v103
	global_store_dwordx4 v237, v[100:103], s[24:25] offset:512
	s_waitcnt vmcnt(31)
	v_lshlrev_b32_e32 v252, 16, v182
	v_and_b32_e32 v182, 0xffff0000, v182
	v_lshlrev_b32_e32 v253, 16, v183
	v_and_b32_e32 v183, 0xffff0000, v183
	v_fma_f32 v92, v252, s14, v92
	v_fma_f32 v93, v182, s14, v93
	v_fma_f32 v94, v253, s14, v94
	v_fma_f32 v95, v183, s14, v95
	global_store_dwordx4 v237, v[92:95], s[24:25] offset:576
	s_waitcnt vmcnt(31)
	v_lshlrev_b32_e32 v252, 16, v184
	v_and_b32_e32 v184, 0xffff0000, v184
	v_lshlrev_b32_e32 v253, 16, v185
	v_and_b32_e32 v185, 0xffff0000, v185
	v_fma_f32 v96, v252, s14, v96
	v_fma_f32 v97, v184, s14, v97
	v_fma_f32 v98, v253, s14, v98
	v_fma_f32 v99, v185, s14, v99
	global_store_dwordx4 v238, v[96:99], s[24:25]
	s_waitcnt vmcnt(31)
	v_lshlrev_b32_e32 v252, 16, v186
	v_and_b32_e32 v186, 0xffff0000, v186
	v_lshlrev_b32_e32 v253, 16, v187
	v_and_b32_e32 v187, 0xffff0000, v187
	v_fma_f32 v88, v252, s14, v88
	v_fma_f32 v89, v186, s14, v89
	v_fma_f32 v90, v253, s14, v90
	v_fma_f32 v91, v187, s14, v91
	global_store_dwordx4 v238, v[88:91], s[24:25] offset:64
	s_waitcnt vmcnt(31)
	v_lshlrev_b32_e32 v252, 16, v188
	v_and_b32_e32 v188, 0xffff0000, v188
	v_lshlrev_b32_e32 v253, 16, v189
	v_and_b32_e32 v189, 0xffff0000, v189
	v_fma_f32 v84, v252, s14, v84
	v_fma_f32 v85, v188, s14, v85
	v_fma_f32 v86, v253, s14, v86
	v_fma_f32 v87, v189, s14, v87
	global_store_dwordx4 v238, v[84:87], s[24:25] offset:512
	s_waitcnt vmcnt(31)
	v_lshlrev_b32_e32 v252, 16, v190
	v_and_b32_e32 v190, 0xffff0000, v190
	v_lshlrev_b32_e32 v253, 16, v191
	v_and_b32_e32 v191, 0xffff0000, v191
	v_fma_f32 v76, v252, s14, v76
	v_fma_f32 v77, v190, s14, v77
	v_fma_f32 v78, v253, s14, v78
	v_fma_f32 v79, v191, s14, v79
	global_store_dwordx4 v238, v[76:79], s[24:25] offset:576
	s_waitcnt vmcnt(31)
	v_lshlrev_b32_e32 v252, 16, v192
	v_and_b32_e32 v192, 0xffff0000, v192
	v_lshlrev_b32_e32 v253, 16, v193
	v_and_b32_e32 v193, 0xffff0000, v193
	v_fma_f32 v80, v252, s14, v80
	v_fma_f32 v81, v192, s14, v81
	v_fma_f32 v82, v253, s14, v82
	v_fma_f32 v83, v193, s14, v83
	global_store_dwordx4 v239, v[80:83], s[24:25]
	s_waitcnt vmcnt(31)
	v_lshlrev_b32_e32 v252, 16, v194
	v_and_b32_e32 v194, 0xffff0000, v194
	v_lshlrev_b32_e32 v253, 16, v195
	v_and_b32_e32 v195, 0xffff0000, v195
	v_fma_f32 v72, v252, s14, v72
	v_fma_f32 v73, v194, s14, v73
	v_fma_f32 v74, v253, s14, v74
	v_fma_f32 v75, v195, s14, v75
	global_store_dwordx4 v239, v[72:75], s[24:25] offset:64
	s_waitcnt vmcnt(31)
	v_lshlrev_b32_e32 v252, 16, v196
	v_and_b32_e32 v196, 0xffff0000, v196
	v_lshlrev_b32_e32 v253, 16, v197
	v_and_b32_e32 v197, 0xffff0000, v197
	v_fma_f32 v68, v252, s14, v68
	v_fma_f32 v69, v196, s14, v69
	v_fma_f32 v70, v253, s14, v70
	v_fma_f32 v71, v197, s14, v71
	global_store_dwordx4 v239, v[68:71], s[24:25] offset:512
	s_waitcnt vmcnt(31)
	v_lshlrev_b32_e32 v252, 16, v198
	v_and_b32_e32 v198, 0xffff0000, v198
	v_lshlrev_b32_e32 v253, 16, v199
	v_and_b32_e32 v199, 0xffff0000, v199
	v_fma_f32 v64, v252, s14, v64
	v_fma_f32 v65, v198, s14, v65
	v_fma_f32 v66, v253, s14, v66
	v_fma_f32 v67, v199, s14, v67
	global_store_dwordx4 v239, v[64:67], s[24:25] offset:576
	s_waitcnt vmcnt(31)
	v_lshlrev_b32_e32 v252, 16, v204
	v_and_b32_e32 v204, 0xffff0000, v204
	v_lshlrev_b32_e32 v253, 16, v205
	v_and_b32_e32 v205, 0xffff0000, v205
	v_fma_f32 v60, v252, s14, v60
	v_fma_f32 v61, v204, s14, v61
	v_fma_f32 v62, v253, s14, v62
	v_fma_f32 v63, v205, s14, v63
	global_store_dwordx4 v240, v[60:63], s[24:25]
	s_waitcnt vmcnt(31)
	v_lshlrev_b32_e32 v252, 16, v206
	v_and_b32_e32 v206, 0xffff0000, v206
	v_lshlrev_b32_e32 v253, 16, v207
	v_and_b32_e32 v207, 0xffff0000, v207
	v_fma_f32 v56, v252, s14, v56
	v_fma_f32 v57, v206, s14, v57
	v_fma_f32 v58, v253, s14, v58
	v_fma_f32 v59, v207, s14, v59
	global_store_dwordx4 v240, v[56:59], s[24:25] offset:64
	s_waitcnt vmcnt(31)
	v_lshlrev_b32_e32 v252, 16, v208
	v_and_b32_e32 v208, 0xffff0000, v208
	v_lshlrev_b32_e32 v253, 16, v209
	v_and_b32_e32 v209, 0xffff0000, v209
	v_fma_f32 v52, v252, s14, v52
	v_fma_f32 v53, v208, s14, v53
	v_fma_f32 v54, v253, s14, v54
	v_fma_f32 v55, v209, s14, v55
	global_store_dwordx4 v240, v[52:55], s[24:25] offset:512
	s_waitcnt vmcnt(31)
	v_lshlrev_b32_e32 v252, 16, v210
	v_and_b32_e32 v210, 0xffff0000, v210
	v_lshlrev_b32_e32 v253, 16, v211
	v_and_b32_e32 v211, 0xffff0000, v211
	v_fma_f32 v44, v252, s14, v44
	v_fma_f32 v45, v210, s14, v45
	v_fma_f32 v46, v253, s14, v46
	v_fma_f32 v47, v211, s14, v47
	global_store_dwordx4 v240, v[44:47], s[24:25] offset:576
	s_waitcnt vmcnt(31)
	v_lshlrev_b32_e32 v252, 16, v212
	v_and_b32_e32 v212, 0xffff0000, v212
	v_lshlrev_b32_e32 v253, 16, v213
	v_and_b32_e32 v213, 0xffff0000, v213
	v_fma_f32 v48, v252, s14, v48
	v_fma_f32 v49, v212, s14, v49
	v_fma_f32 v50, v253, s14, v50
	v_fma_f32 v51, v213, s14, v51
	global_store_dwordx4 v241, v[48:51], s[24:25]
	s_waitcnt vmcnt(31)
	v_lshlrev_b32_e32 v252, 16, v214
	v_and_b32_e32 v214, 0xffff0000, v214
	v_lshlrev_b32_e32 v253, 16, v215
	v_and_b32_e32 v215, 0xffff0000, v215
	v_fma_f32 v40, v252, s14, v40
	v_fma_f32 v41, v214, s14, v41
	v_fma_f32 v42, v253, s14, v42
	v_fma_f32 v43, v215, s14, v43
	global_store_dwordx4 v241, v[40:43], s[24:25] offset:64
	s_waitcnt vmcnt(31)
	v_lshlrev_b32_e32 v252, 16, v216
	v_and_b32_e32 v216, 0xffff0000, v216
	v_lshlrev_b32_e32 v253, 16, v217
	v_and_b32_e32 v217, 0xffff0000, v217
	v_fma_f32 v36, v252, s14, v36
	v_fma_f32 v37, v216, s14, v37
	v_fma_f32 v38, v253, s14, v38
	v_fma_f32 v39, v217, s14, v39
	global_store_dwordx4 v241, v[36:39], s[24:25] offset:512
	s_waitcnt vmcnt(31)
	v_lshlrev_b32_e32 v252, 16, v218
	v_and_b32_e32 v218, 0xffff0000, v218
	v_lshlrev_b32_e32 v253, 16, v219
	v_and_b32_e32 v219, 0xffff0000, v219
	v_fma_f32 v28, v252, s14, v28
	v_fma_f32 v29, v218, s14, v29
	v_fma_f32 v30, v253, s14, v30
	v_fma_f32 v31, v219, s14, v31
	global_store_dwordx4 v241, v[28:31], s[24:25] offset:576
	s_waitcnt vmcnt(31)
	v_lshlrev_b32_e32 v252, 16, v220
	v_and_b32_e32 v220, 0xffff0000, v220
	v_lshlrev_b32_e32 v253, 16, v221
	v_and_b32_e32 v221, 0xffff0000, v221
	v_fma_f32 v32, v252, s14, v32
	v_fma_f32 v33, v220, s14, v33
	v_fma_f32 v34, v253, s14, v34
	v_fma_f32 v35, v221, s14, v35
	global_store_dwordx4 v242, v[32:35], s[24:25]
	s_waitcnt vmcnt(31)
	v_lshlrev_b32_e32 v252, 16, v222
	v_and_b32_e32 v222, 0xffff0000, v222
	v_lshlrev_b32_e32 v253, 16, v223
	v_and_b32_e32 v223, 0xffff0000, v223
	v_fma_f32 v24, v252, s14, v24
	v_fma_f32 v25, v222, s14, v25
	v_fma_f32 v26, v253, s14, v26
	v_fma_f32 v27, v223, s14, v27
	global_store_dwordx4 v242, v[24:27], s[24:25] offset:64
	s_waitcnt vmcnt(31)
	v_lshlrev_b32_e32 v252, 16, v224
	v_and_b32_e32 v224, 0xffff0000, v224
	v_lshlrev_b32_e32 v253, 16, v225
	v_and_b32_e32 v225, 0xffff0000, v225
	v_fma_f32 v20, v252, s14, v20
	v_fma_f32 v21, v224, s14, v21
	v_fma_f32 v22, v253, s14, v22
	v_fma_f32 v23, v225, s14, v23
	global_store_dwordx4 v242, v[20:23], s[24:25] offset:512
	s_waitcnt vmcnt(31)
	v_lshlrev_b32_e32 v252, 16, v226
	v_and_b32_e32 v226, 0xffff0000, v226
	v_lshlrev_b32_e32 v253, 16, v227
	v_and_b32_e32 v227, 0xffff0000, v227
	v_fma_f32 v12, v252, s14, v12
	v_fma_f32 v13, v226, s14, v13
	v_fma_f32 v14, v253, s14, v14
	v_fma_f32 v15, v227, s14, v15
	global_store_dwordx4 v242, v[12:15], s[24:25] offset:576
	s_waitcnt vmcnt(31)
	v_lshlrev_b32_e32 v252, 16, v228
	v_and_b32_e32 v228, 0xffff0000, v228
	v_lshlrev_b32_e32 v253, 16, v229
	v_and_b32_e32 v229, 0xffff0000, v229
	v_fma_f32 v16, v252, s14, v16
	v_fma_f32 v17, v228, s14, v17
	v_fma_f32 v18, v253, s14, v18
	v_fma_f32 v19, v229, s14, v19
	global_store_dwordx4 v243, v[16:19], s[24:25]
	s_waitcnt vmcnt(31)
	v_lshlrev_b32_e32 v252, 16, v230
	v_and_b32_e32 v230, 0xffff0000, v230
	v_lshlrev_b32_e32 v253, 16, v231
	v_and_b32_e32 v231, 0xffff0000, v231
	v_fma_f32 v8, v252, s14, v8
	v_fma_f32 v9, v230, s14, v9
	v_fma_f32 v10, v253, s14, v10
	v_fma_f32 v11, v231, s14, v11
	global_store_dwordx4 v243, v[8:11], s[24:25] offset:64
	s_waitcnt vmcnt(31)
	v_lshlrev_b32_e32 v252, 16, v232
	v_and_b32_e32 v232, 0xffff0000, v232
	v_lshlrev_b32_e32 v253, 16, v233
	v_and_b32_e32 v233, 0xffff0000, v233
	v_fma_f32 v4, v252, s14, v4
	v_fma_f32 v5, v232, s14, v5
	v_fma_f32 v6, v253, s14, v6
	v_fma_f32 v7, v233, s14, v7
	global_store_dwordx4 v243, v[4:7], s[24:25] offset:512
	s_waitcnt vmcnt(31)
	v_lshlrev_b32_e32 v252, 16, v234
	v_and_b32_e32 v234, 0xffff0000, v234
	v_lshlrev_b32_e32 v253, 16, v235
	v_and_b32_e32 v235, 0xffff0000, v235
	v_fma_f32 v0, v252, s14, v0
	v_fma_f32 v1, v234, s14, v1
	v_fma_f32 v2, v253, s14, v2
	v_fma_f32 v3, v235, s14, v3
	global_store_dwordx4 v243, v[0:3], s[24:25] offset:576
	s_cbranch_vccnz .LBB0_1010
	s_andn2_b64 vcc, exec, s[6:7]
	s_cbranch_vccnz .LBB0_1009
	s_barrier
	s_branch .LBB0_1009

.LBB0_1418:
	v_lshl_add_u32 v144, s1, 8, v146
	v_lshl_or_b32 v142, s0, 8, v148
	v_ashrrev_i32_e32 v145, 31, v144
	v_ashrrev_i32_e32 v143, 31, v142
	v_lshl_add_u32 v252, v144, 10, v142
	v_lshlrev_b32_e32 v252, 2, v252
	v_mov_b32_e32 v236, v252
	v_lshrrev_b32_e32 v244, 1, v236
	v_add_u32_e32 v237, 0x10000, v252
	v_lshrrev_b32_e32 v245, 1, v237
	v_add_u32_e32 v238, 0x20000, v252
	v_lshrrev_b32_e32 v246, 1, v238
	v_add_u32_e32 v239, 0x30000, v252
	v_lshrrev_b32_e32 v247, 1, v239
	v_lshl_add_u32 v240, s14, 2, v252
	v_lshrrev_b32_e32 v248, 1, v240
	v_lshl_add_u32 v241, s18, 2, v252
	v_lshrrev_b32_e32 v249, 1, v241
	v_lshl_add_u32 v242, s20, 2, v252
	v_lshrrev_b32_e32 v250, 1, v242
	v_lshl_add_u32 v243, s34, 2, v252
	v_lshrrev_b32_e32 v251, 1, v243
	s_andn2_b64 vcc, exec, s[2:3]
	s_mov_b64 s[2:3], -1
	global_load_dwordx2 v[168:169], v244, s[6:7]
	global_load_dwordx2 v[170:171], v244, s[6:7] offset:32
	global_load_dwordx2 v[172:173], v244, s[6:7] offset:256
	global_load_dwordx2 v[174:175], v244, s[6:7] offset:288
	global_load_dwordx2 v[176:177], v245, s[6:7]
	global_load_dwordx2 v[178:179], v245, s[6:7] offset:32
	global_load_dwordx2 v[180:181], v245, s[6:7] offset:256
	global_load_dwordx2 v[182:183], v245, s[6:7] offset:288
	global_load_dwordx2 v[184:185], v246, s[6:7]
	global_load_dwordx2 v[186:187], v246, s[6:7] offset:32
	global_load_dwordx2 v[188:189], v246, s[6:7] offset:256
	global_load_dwordx2 v[190:191], v246, s[6:7] offset:288
	global_load_dwordx2 v[192:193], v247, s[6:7]
	global_load_dwordx2 v[194:195], v247, s[6:7] offset:32
	global_load_dwordx2 v[196:197], v247, s[6:7] offset:256
	global_load_dwordx2 v[198:199], v247, s[6:7] offset:288
	global_load_dwordx2 v[204:205], v248, s[6:7]
	global_load_dwordx2 v[206:207], v248, s[6:7] offset:32
	global_load_dwordx2 v[208:209], v248, s[6:7] offset:256
	global_load_dwordx2 v[210:211], v248, s[6:7] offset:288
	global_load_dwordx2 v[212:213], v249, s[6:7]
	global_load_dwordx2 v[214:215], v249, s[6:7] offset:32
	global_load_dwordx2 v[216:217], v249, s[6:7] offset:256
	global_load_dwordx2 v[218:219], v249, s[6:7] offset:288
	global_load_dwordx2 v[220:221], v250, s[6:7]
	global_load_dwordx2 v[222:223], v250, s[6:7] offset:32
	global_load_dwordx2 v[224:225], v250, s[6:7] offset:256
	global_load_dwordx2 v[226:227], v250, s[6:7] offset:288
	global_load_dwordx2 v[228:229], v251, s[6:7]
	global_load_dwordx2 v[230:231], v251, s[6:7] offset:32
	global_load_dwordx2 v[232:233], v251, s[6:7] offset:256
	global_load_dwordx2 v[234:235], v251, s[6:7] offset:288
	s_waitcnt vmcnt(31)
	v_lshlrev_b32_e32 v252, 16, v168
	v_and_b32_e32 v168, 0xffff0000, v168
	v_lshlrev_b32_e32 v253, 16, v169
	v_and_b32_e32 v169, 0xffff0000, v169
	v_fma_f32 v124, v252, s12, v124
	v_fma_f32 v125, v168, s12, v125
	v_fma_f32 v126, v253, s12, v126
	v_fma_f32 v127, v169, s12, v127
	global_store_dwordx4 v236, v[124:127], s[24:25]
	s_waitcnt vmcnt(31)
	v_lshlrev_b32_e32 v252, 16, v170
	v_and_b32_e32 v170, 0xffff0000, v170
	v_lshlrev_b32_e32 v253, 16, v171
	v_and_b32_e32 v171, 0xffff0000, v171
	v_fma_f32 v120, v252, s12, v120
	v_fma_f32 v121, v170, s12, v121
	v_fma_f32 v122, v253, s12, v122
	v_fma_f32 v123, v171, s12, v123
	global_store_dwordx4 v236, v[120:123], s[24:25] offset:64
	s_waitcnt vmcnt(31)
	v_lshlrev_b32_e32 v252, 16, v172
	v_and_b32_e32 v172, 0xffff0000, v172
	v_lshlrev_b32_e32 v253, 16, v173
	v_and_b32_e32 v173, 0xffff0000, v173
	v_fma_f32 v116, v252, s12, v116
	v_fma_f32 v117, v172, s12, v117
	v_fma_f32 v118, v253, s12, v118
	v_fma_f32 v119, v173, s12, v119
	global_store_dwordx4 v236, v[116:119], s[24:25] offset:512
	s_waitcnt vmcnt(31)
	v_lshlrev_b32_e32 v252, 16, v174
	v_and_b32_e32 v174, 0xffff0000, v174
	v_lshlrev_b32_e32 v253, 16, v175
	v_and_b32_e32 v175, 0xffff0000, v175
	v_fma_f32 v108, v252, s12, v108
	v_fma_f32 v109, v174, s12, v109
	v_fma_f32 v110, v253, s12, v110
	v_fma_f32 v111, v175, s12, v111
	global_store_dwordx4 v236, v[108:111], s[24:25] offset:576
	s_waitcnt vmcnt(31)
	v_lshlrev_b32_e32 v252, 16, v176
	v_and_b32_e32 v176, 0xffff0000, v176
	v_lshlrev_b32_e32 v253, 16, v177
	v_and_b32_e32 v177, 0xffff0000, v177
	v_fma_f32 v112, v252, s12, v112
	v_fma_f32 v113, v176, s12, v113
	v_fma_f32 v114, v253, s12, v114
	v_fma_f32 v115, v177, s12, v115
	global_store_dwordx4 v237, v[112:115], s[24:25]
	s_waitcnt vmcnt(31)
	v_lshlrev_b32_e32 v252, 16, v178
	v_and_b32_e32 v178, 0xffff0000, v178
	v_lshlrev_b32_e32 v253, 16, v179
	v_and_b32_e32 v179, 0xffff0000, v179
	v_fma_f32 v104, v252, s12, v104
	v_fma_f32 v105, v178, s12, v105
	v_fma_f32 v106, v253, s12, v106
	v_fma_f32 v107, v179, s12, v107
	global_store_dwordx4 v237, v[104:107], s[24:25] offset:64
	s_waitcnt vmcnt(31)
	v_lshlrev_b32_e32 v252, 16, v180
	v_and_b32_e32 v180, 0xffff0000, v180
	v_lshlrev_b32_e32 v253, 16, v181
	v_and_b32_e32 v181, 0xffff0000, v181
	v_fma_f32 v100, v252, s12, v100
	v_fma_f32 v101, v180, s12, v101
	v_fma_f32 v102, v253, s12, v102
	v_fma_f32 v103, v181, s12, v103
	global_store_dwordx4 v237, v[100:103], s[24:25] offset:512
	s_waitcnt vmcnt(31)
	v_lshlrev_b32_e32 v252, 16, v182
	v_and_b32_e32 v182, 0xffff0000, v182
	v_lshlrev_b32_e32 v253, 16, v183
	v_and_b32_e32 v183, 0xffff0000, v183
	v_fma_f32 v92, v252, s12, v92
	v_fma_f32 v93, v182, s12, v93
	v_fma_f32 v94, v253, s12, v94
	v_fma_f32 v95, v183, s12, v95
	global_store_dwordx4 v237, v[92:95], s[24:25] offset:576
	s_waitcnt vmcnt(31)
	v_lshlrev_b32_e32 v252, 16, v184
	v_and_b32_e32 v184, 0xffff0000, v184
	v_lshlrev_b32_e32 v253, 16, v185
	v_and_b32_e32 v185, 0xffff0000, v185
	v_fma_f32 v96, v252, s12, v96
	v_fma_f32 v97, v184, s12, v97
	v_fma_f32 v98, v253, s12, v98
	v_fma_f32 v99, v185, s12, v99
	global_store_dwordx4 v238, v[96:99], s[24:25]
	s_waitcnt vmcnt(31)
	v_lshlrev_b32_e32 v252, 16, v186
	v_and_b32_e32 v186, 0xffff0000, v186
	v_lshlrev_b32_e32 v253, 16, v187
	v_and_b32_e32 v187, 0xffff0000, v187
	v_fma_f32 v88, v252, s12, v88
	v_fma_f32 v89, v186, s12, v89
	v_fma_f32 v90, v253, s12, v90
	v_fma_f32 v91, v187, s12, v91
	global_store_dwordx4 v238, v[88:91], s[24:25] offset:64
	s_waitcnt vmcnt(31)
	v_lshlrev_b32_e32 v252, 16, v188
	v_and_b32_e32 v188, 0xffff0000, v188
	v_lshlrev_b32_e32 v253, 16, v189
	v_and_b32_e32 v189, 0xffff0000, v189
	v_fma_f32 v84, v252, s12, v84
	v_fma_f32 v85, v188, s12, v85
	v_fma_f32 v86, v253, s12, v86
	v_fma_f32 v87, v189, s12, v87
	global_store_dwordx4 v238, v[84:87], s[24:25] offset:512
	s_waitcnt vmcnt(31)
	v_lshlrev_b32_e32 v252, 16, v190
	v_and_b32_e32 v190, 0xffff0000, v190
	v_lshlrev_b32_e32 v253, 16, v191
	v_and_b32_e32 v191, 0xffff0000, v191
	v_fma_f32 v76, v252, s12, v76
	v_fma_f32 v77, v190, s12, v77
	v_fma_f32 v78, v253, s12, v78
	v_fma_f32 v79, v191, s12, v79
	global_store_dwordx4 v238, v[76:79], s[24:25] offset:576
	s_waitcnt vmcnt(31)
	v_lshlrev_b32_e32 v252, 16, v192
	v_and_b32_e32 v192, 0xffff0000, v192
	v_lshlrev_b32_e32 v253, 16, v193
	v_and_b32_e32 v193, 0xffff0000, v193
	v_fma_f32 v80, v252, s12, v80
	v_fma_f32 v81, v192, s12, v81
	v_fma_f32 v82, v253, s12, v82
	v_fma_f32 v83, v193, s12, v83
	global_store_dwordx4 v239, v[80:83], s[24:25]
	s_waitcnt vmcnt(31)
	v_lshlrev_b32_e32 v252, 16, v194
	v_and_b32_e32 v194, 0xffff0000, v194
	v_lshlrev_b32_e32 v253, 16, v195
	v_and_b32_e32 v195, 0xffff0000, v195
	v_fma_f32 v72, v252, s12, v72
	v_fma_f32 v73, v194, s12, v73
	v_fma_f32 v74, v253, s12, v74
	v_fma_f32 v75, v195, s12, v75
	global_store_dwordx4 v239, v[72:75], s[24:25] offset:64
	s_waitcnt vmcnt(31)
	v_lshlrev_b32_e32 v252, 16, v196
	v_and_b32_e32 v196, 0xffff0000, v196
	v_lshlrev_b32_e32 v253, 16, v197
	v_and_b32_e32 v197, 0xffff0000, v197
	v_fma_f32 v68, v252, s12, v68
	v_fma_f32 v69, v196, s12, v69
	v_fma_f32 v70, v253, s12, v70
	v_fma_f32 v71, v197, s12, v71
	global_store_dwordx4 v239, v[68:71], s[24:25] offset:512
	s_waitcnt vmcnt(31)
	v_lshlrev_b32_e32 v252, 16, v198
	v_and_b32_e32 v198, 0xffff0000, v198
	v_lshlrev_b32_e32 v253, 16, v199
	v_and_b32_e32 v199, 0xffff0000, v199
	v_fma_f32 v64, v252, s12, v64
	v_fma_f32 v65, v198, s12, v65
	v_fma_f32 v66, v253, s12, v66
	v_fma_f32 v67, v199, s12, v67
	global_store_dwordx4 v239, v[64:67], s[24:25] offset:576
	s_waitcnt vmcnt(31)
	v_lshlrev_b32_e32 v252, 16, v204
	v_and_b32_e32 v204, 0xffff0000, v204
	v_lshlrev_b32_e32 v253, 16, v205
	v_and_b32_e32 v205, 0xffff0000, v205
	v_fma_f32 v60, v252, s12, v60
	v_fma_f32 v61, v204, s12, v61
	v_fma_f32 v62, v253, s12, v62
	v_fma_f32 v63, v205, s12, v63
	global_store_dwordx4 v240, v[60:63], s[24:25]
	s_waitcnt vmcnt(31)
	v_lshlrev_b32_e32 v252, 16, v206
	v_and_b32_e32 v206, 0xffff0000, v206
	v_lshlrev_b32_e32 v253, 16, v207
	v_and_b32_e32 v207, 0xffff0000, v207
	v_fma_f32 v56, v252, s12, v56
	v_fma_f32 v57, v206, s12, v57
	v_fma_f32 v58, v253, s12, v58
	v_fma_f32 v59, v207, s12, v59
	global_store_dwordx4 v240, v[56:59], s[24:25] offset:64
	s_waitcnt vmcnt(31)
	v_lshlrev_b32_e32 v252, 16, v208
	v_and_b32_e32 v208, 0xffff0000, v208
	v_lshlrev_b32_e32 v253, 16, v209
	v_and_b32_e32 v209, 0xffff0000, v209
	v_fma_f32 v52, v252, s12, v52
	v_fma_f32 v53, v208, s12, v53
	v_fma_f32 v54, v253, s12, v54
	v_fma_f32 v55, v209, s12, v55
	global_store_dwordx4 v240, v[52:55], s[24:25] offset:512
	s_waitcnt vmcnt(31)
	v_lshlrev_b32_e32 v252, 16, v210
	v_and_b32_e32 v210, 0xffff0000, v210
	v_lshlrev_b32_e32 v253, 16, v211
	v_and_b32_e32 v211, 0xffff0000, v211
	v_fma_f32 v44, v252, s12, v44
	v_fma_f32 v45, v210, s12, v45
	v_fma_f32 v46, v253, s12, v46
	v_fma_f32 v47, v211, s12, v47
	global_store_dwordx4 v240, v[44:47], s[24:25] offset:576
	s_waitcnt vmcnt(31)
	v_lshlrev_b32_e32 v252, 16, v212
	v_and_b32_e32 v212, 0xffff0000, v212
	v_lshlrev_b32_e32 v253, 16, v213
	v_and_b32_e32 v213, 0xffff0000, v213
	v_fma_f32 v48, v252, s12, v48
	v_fma_f32 v49, v212, s12, v49
	v_fma_f32 v50, v253, s12, v50
	v_fma_f32 v51, v213, s12, v51
	global_store_dwordx4 v241, v[48:51], s[24:25]
	s_waitcnt vmcnt(31)
	v_lshlrev_b32_e32 v252, 16, v214
	v_and_b32_e32 v214, 0xffff0000, v214
	v_lshlrev_b32_e32 v253, 16, v215
	v_and_b32_e32 v215, 0xffff0000, v215
	v_fma_f32 v40, v252, s12, v40
	v_fma_f32 v41, v214, s12, v41
	v_fma_f32 v42, v253, s12, v42
	v_fma_f32 v43, v215, s12, v43
	global_store_dwordx4 v241, v[40:43], s[24:25] offset:64
	s_waitcnt vmcnt(31)
	v_lshlrev_b32_e32 v252, 16, v216
	v_and_b32_e32 v216, 0xffff0000, v216
	v_lshlrev_b32_e32 v253, 16, v217
	v_and_b32_e32 v217, 0xffff0000, v217
	v_fma_f32 v36, v252, s12, v36
	v_fma_f32 v37, v216, s12, v37
	v_fma_f32 v38, v253, s12, v38
	v_fma_f32 v39, v217, s12, v39
	global_store_dwordx4 v241, v[36:39], s[24:25] offset:512
	s_waitcnt vmcnt(31)
	v_lshlrev_b32_e32 v252, 16, v218
	v_and_b32_e32 v218, 0xffff0000, v218
	v_lshlrev_b32_e32 v253, 16, v219
	v_and_b32_e32 v219, 0xffff0000, v219
	v_fma_f32 v28, v252, s12, v28
	v_fma_f32 v29, v218, s12, v29
	v_fma_f32 v30, v253, s12, v30
	v_fma_f32 v31, v219, s12, v31
	global_store_dwordx4 v241, v[28:31], s[24:25] offset:576
	s_waitcnt vmcnt(31)
	v_lshlrev_b32_e32 v252, 16, v220
	v_and_b32_e32 v220, 0xffff0000, v220
	v_lshlrev_b32_e32 v253, 16, v221
	v_and_b32_e32 v221, 0xffff0000, v221
	v_fma_f32 v32, v252, s12, v32
	v_fma_f32 v33, v220, s12, v33
	v_fma_f32 v34, v253, s12, v34
	v_fma_f32 v35, v221, s12, v35
	global_store_dwordx4 v242, v[32:35], s[24:25]
	s_waitcnt vmcnt(31)
	v_lshlrev_b32_e32 v252, 16, v222
	v_and_b32_e32 v222, 0xffff0000, v222
	v_lshlrev_b32_e32 v253, 16, v223
	v_and_b32_e32 v223, 0xffff0000, v223
	v_fma_f32 v24, v252, s12, v24
	v_fma_f32 v25, v222, s12, v25
	v_fma_f32 v26, v253, s12, v26
	v_fma_f32 v27, v223, s12, v27
	global_store_dwordx4 v242, v[24:27], s[24:25] offset:64
	s_waitcnt vmcnt(31)
	v_lshlrev_b32_e32 v252, 16, v224
	v_and_b32_e32 v224, 0xffff0000, v224
	v_lshlrev_b32_e32 v253, 16, v225
	v_and_b32_e32 v225, 0xffff0000, v225
	v_fma_f32 v20, v252, s12, v20
	v_fma_f32 v21, v224, s12, v21
	v_fma_f32 v22, v253, s12, v22
	v_fma_f32 v23, v225, s12, v23
	global_store_dwordx4 v242, v[20:23], s[24:25] offset:512
	s_waitcnt vmcnt(31)
	v_lshlrev_b32_e32 v252, 16, v226
	v_and_b32_e32 v226, 0xffff0000, v226
	v_lshlrev_b32_e32 v253, 16, v227
	v_and_b32_e32 v227, 0xffff0000, v227
	v_fma_f32 v12, v252, s12, v12
	v_fma_f32 v13, v226, s12, v13
	v_fma_f32 v14, v253, s12, v14
	v_fma_f32 v15, v227, s12, v15
	global_store_dwordx4 v242, v[12:15], s[24:25] offset:576
	s_waitcnt vmcnt(31)
	v_lshlrev_b32_e32 v252, 16, v228
	v_and_b32_e32 v228, 0xffff0000, v228
	v_lshlrev_b32_e32 v253, 16, v229
	v_and_b32_e32 v229, 0xffff0000, v229
	v_fma_f32 v16, v252, s12, v16
	v_fma_f32 v17, v228, s12, v17
	v_fma_f32 v18, v253, s12, v18
	v_fma_f32 v19, v229, s12, v19
	global_store_dwordx4 v243, v[16:19], s[24:25]
	s_waitcnt vmcnt(31)
	v_lshlrev_b32_e32 v252, 16, v230
	v_and_b32_e32 v230, 0xffff0000, v230
	v_lshlrev_b32_e32 v253, 16, v231
	v_and_b32_e32 v231, 0xffff0000, v231
	v_fma_f32 v8, v252, s12, v8
	v_fma_f32 v9, v230, s12, v9
	v_fma_f32 v10, v253, s12, v10
	v_fma_f32 v11, v231, s12, v11
	global_store_dwordx4 v243, v[8:11], s[24:25] offset:64
	s_waitcnt vmcnt(31)
	v_lshlrev_b32_e32 v252, 16, v232
	v_and_b32_e32 v232, 0xffff0000, v232
	v_lshlrev_b32_e32 v253, 16, v233
	v_and_b32_e32 v233, 0xffff0000, v233
	v_fma_f32 v4, v252, s12, v4
	v_fma_f32 v5, v232, s12, v5
	v_fma_f32 v6, v253, s12, v6
	v_fma_f32 v7, v233, s12, v7
	global_store_dwordx4 v243, v[4:7], s[24:25] offset:512
	s_waitcnt vmcnt(31)
	v_lshlrev_b32_e32 v252, 16, v234
	v_and_b32_e32 v234, 0xffff0000, v234
	v_lshlrev_b32_e32 v253, 16, v235
	v_and_b32_e32 v235, 0xffff0000, v235
	v_fma_f32 v0, v252, s12, v0
	v_fma_f32 v1, v234, s12, v1
	v_fma_f32 v2, v253, s12, v2
	v_fma_f32 v3, v235, s12, v3
	global_store_dwordx4 v243, v[0:3], s[24:25] offset:576
	s_cbranch_vccnz .LBB0_1411
	s_andn2_b64 vcc, exec, s[4:5]
	s_cbranch_vccnz .LBB0_1410
	s_barrier
	s_branch .LBB0_1410

.LBB0_1707:
	v_lshl_add_u32 v144, s1, 8, v146
	v_lshl_or_b32 v142, s0, 8, v148
	v_ashrrev_i32_e32 v145, 31, v144
	v_ashrrev_i32_e32 v143, 31, v142
	v_lshl_add_u32 v252, v144, 10, v142
	v_lshlrev_b32_e32 v252, 2, v252
	v_mov_b32_e32 v236, v252
	v_lshrrev_b32_e32 v244, 1, v236
	v_add_u32_e32 v237, 0x10000, v252
	v_lshrrev_b32_e32 v245, 1, v237
	v_add_u32_e32 v238, 0x20000, v252
	v_lshrrev_b32_e32 v246, 1, v238
	v_add_u32_e32 v239, 0x30000, v252
	v_lshrrev_b32_e32 v247, 1, v239
	v_lshl_add_u32 v240, s18, 2, v252
	v_lshrrev_b32_e32 v248, 1, v240
	v_lshl_add_u32 v241, s20, 2, v252
	v_lshrrev_b32_e32 v249, 1, v241
	v_lshl_add_u32 v242, s34, 2, v252
	v_lshrrev_b32_e32 v250, 1, v242
	v_lshl_add_u32 v243, s36, 2, v252
	v_lshrrev_b32_e32 v251, 1, v243
	s_and_b64 vcc, exec, s[2:3]
	s_mov_b64 s[2:3], -1
	global_load_dwordx2 v[168:169], v244, s[8:9]
	global_load_dwordx2 v[170:171], v244, s[8:9] offset:32
	global_load_dwordx2 v[172:173], v244, s[8:9] offset:256
	global_load_dwordx2 v[174:175], v244, s[8:9] offset:288
	global_load_dwordx2 v[176:177], v245, s[8:9]
	global_load_dwordx2 v[178:179], v245, s[8:9] offset:32
	global_load_dwordx2 v[180:181], v245, s[8:9] offset:256
	global_load_dwordx2 v[182:183], v245, s[8:9] offset:288
	global_load_dwordx2 v[184:185], v246, s[8:9]
	global_load_dwordx2 v[186:187], v246, s[8:9] offset:32
	global_load_dwordx2 v[188:189], v246, s[8:9] offset:256
	global_load_dwordx2 v[190:191], v246, s[8:9] offset:288
	global_load_dwordx2 v[192:193], v247, s[8:9]
	global_load_dwordx2 v[194:195], v247, s[8:9] offset:32
	global_load_dwordx2 v[196:197], v247, s[8:9] offset:256
	global_load_dwordx2 v[198:199], v247, s[8:9] offset:288
	global_load_dwordx2 v[204:205], v248, s[8:9]
	global_load_dwordx2 v[206:207], v248, s[8:9] offset:32
	global_load_dwordx2 v[208:209], v248, s[8:9] offset:256
	global_load_dwordx2 v[210:211], v248, s[8:9] offset:288
	global_load_dwordx2 v[212:213], v249, s[8:9]
	global_load_dwordx2 v[214:215], v249, s[8:9] offset:32
	global_load_dwordx2 v[216:217], v249, s[8:9] offset:256
	global_load_dwordx2 v[218:219], v249, s[8:9] offset:288
	global_load_dwordx2 v[220:221], v250, s[8:9]
	global_load_dwordx2 v[222:223], v250, s[8:9] offset:32
	global_load_dwordx2 v[224:225], v250, s[8:9] offset:256
	global_load_dwordx2 v[226:227], v250, s[8:9] offset:288
	global_load_dwordx2 v[228:229], v251, s[8:9]
	global_load_dwordx2 v[230:231], v251, s[8:9] offset:32
	global_load_dwordx2 v[232:233], v251, s[8:9] offset:256
	global_load_dwordx2 v[234:235], v251, s[8:9] offset:288
	s_waitcnt vmcnt(31)
	v_lshlrev_b32_e32 v252, 16, v168
	v_and_b32_e32 v168, 0xffff0000, v168
	v_lshlrev_b32_e32 v253, 16, v169
	v_and_b32_e32 v169, 0xffff0000, v169
	v_fma_f32 v124, v252, s14, v124
	v_fma_f32 v125, v168, s14, v125
	v_fma_f32 v126, v253, s14, v126
	v_fma_f32 v127, v169, s14, v127
	global_store_dwordx4 v236, v[124:127], s[24:25]
	s_waitcnt vmcnt(31)
	v_lshlrev_b32_e32 v252, 16, v170
	v_and_b32_e32 v170, 0xffff0000, v170
	v_lshlrev_b32_e32 v253, 16, v171
	v_and_b32_e32 v171, 0xffff0000, v171
	v_fma_f32 v120, v252, s14, v120
	v_fma_f32 v121, v170, s14, v121
	v_fma_f32 v122, v253, s14, v122
	v_fma_f32 v123, v171, s14, v123
	global_store_dwordx4 v236, v[120:123], s[24:25] offset:64
	s_waitcnt vmcnt(31)
	v_lshlrev_b32_e32 v252, 16, v172
	v_and_b32_e32 v172, 0xffff0000, v172
	v_lshlrev_b32_e32 v253, 16, v173
	v_and_b32_e32 v173, 0xffff0000, v173
	v_fma_f32 v116, v252, s14, v116
	v_fma_f32 v117, v172, s14, v117
	v_fma_f32 v118, v253, s14, v118
	v_fma_f32 v119, v173, s14, v119
	global_store_dwordx4 v236, v[116:119], s[24:25] offset:512
	s_waitcnt vmcnt(31)
	v_lshlrev_b32_e32 v252, 16, v174
	v_and_b32_e32 v174, 0xffff0000, v174
	v_lshlrev_b32_e32 v253, 16, v175
	v_and_b32_e32 v175, 0xffff0000, v175
	v_fma_f32 v108, v252, s14, v108
	v_fma_f32 v109, v174, s14, v109
	v_fma_f32 v110, v253, s14, v110
	v_fma_f32 v111, v175, s14, v111
	global_store_dwordx4 v236, v[108:111], s[24:25] offset:576
	s_waitcnt vmcnt(31)
	v_lshlrev_b32_e32 v252, 16, v176
	v_and_b32_e32 v176, 0xffff0000, v176
	v_lshlrev_b32_e32 v253, 16, v177
	v_and_b32_e32 v177, 0xffff0000, v177
	v_fma_f32 v112, v252, s14, v112
	v_fma_f32 v113, v176, s14, v113
	v_fma_f32 v114, v253, s14, v114
	v_fma_f32 v115, v177, s14, v115
	global_store_dwordx4 v237, v[112:115], s[24:25]
	s_waitcnt vmcnt(31)
	v_lshlrev_b32_e32 v252, 16, v178
	v_and_b32_e32 v178, 0xffff0000, v178
	v_lshlrev_b32_e32 v253, 16, v179
	v_and_b32_e32 v179, 0xffff0000, v179
	v_fma_f32 v104, v252, s14, v104
	v_fma_f32 v105, v178, s14, v105
	v_fma_f32 v106, v253, s14, v106
	v_fma_f32 v107, v179, s14, v107
	global_store_dwordx4 v237, v[104:107], s[24:25] offset:64
	s_waitcnt vmcnt(31)
	v_lshlrev_b32_e32 v252, 16, v180
	v_and_b32_e32 v180, 0xffff0000, v180
	v_lshlrev_b32_e32 v253, 16, v181
	v_and_b32_e32 v181, 0xffff0000, v181
	v_fma_f32 v100, v252, s14, v100
	v_fma_f32 v101, v180, s14, v101
	v_fma_f32 v102, v253, s14, v102
	v_fma_f32 v103, v181, s14, v103
	global_store_dwordx4 v237, v[100:103], s[24:25] offset:512
	s_waitcnt vmcnt(31)
	v_lshlrev_b32_e32 v252, 16, v182
	v_and_b32_e32 v182, 0xffff0000, v182
	v_lshlrev_b32_e32 v253, 16, v183
	v_and_b32_e32 v183, 0xffff0000, v183
	v_fma_f32 v92, v252, s14, v92
	v_fma_f32 v93, v182, s14, v93
	v_fma_f32 v94, v253, s14, v94
	v_fma_f32 v95, v183, s14, v95
	global_store_dwordx4 v237, v[92:95], s[24:25] offset:576
	s_waitcnt vmcnt(31)
	v_lshlrev_b32_e32 v252, 16, v184
	v_and_b32_e32 v184, 0xffff0000, v184
	v_lshlrev_b32_e32 v253, 16, v185
	v_and_b32_e32 v185, 0xffff0000, v185
	v_fma_f32 v96, v252, s14, v96
	v_fma_f32 v97, v184, s14, v97
	v_fma_f32 v98, v253, s14, v98
	v_fma_f32 v99, v185, s14, v99
	global_store_dwordx4 v238, v[96:99], s[24:25]
	s_waitcnt vmcnt(31)
	v_lshlrev_b32_e32 v252, 16, v186
	v_and_b32_e32 v186, 0xffff0000, v186
	v_lshlrev_b32_e32 v253, 16, v187
	v_and_b32_e32 v187, 0xffff0000, v187
	v_fma_f32 v88, v252, s14, v88
	v_fma_f32 v89, v186, s14, v89
	v_fma_f32 v90, v253, s14, v90
	v_fma_f32 v91, v187, s14, v91
	global_store_dwordx4 v238, v[88:91], s[24:25] offset:64
	s_waitcnt vmcnt(31)
	v_lshlrev_b32_e32 v252, 16, v188
	v_and_b32_e32 v188, 0xffff0000, v188
	v_lshlrev_b32_e32 v253, 16, v189
	v_and_b32_e32 v189, 0xffff0000, v189
	v_fma_f32 v84, v252, s14, v84
	v_fma_f32 v85, v188, s14, v85
	v_fma_f32 v86, v253, s14, v86
	v_fma_f32 v87, v189, s14, v87
	global_store_dwordx4 v238, v[84:87], s[24:25] offset:512
	s_waitcnt vmcnt(31)
	v_lshlrev_b32_e32 v252, 16, v190
	v_and_b32_e32 v190, 0xffff0000, v190
	v_lshlrev_b32_e32 v253, 16, v191
	v_and_b32_e32 v191, 0xffff0000, v191
	v_fma_f32 v76, v252, s14, v76
	v_fma_f32 v77, v190, s14, v77
	v_fma_f32 v78, v253, s14, v78
	v_fma_f32 v79, v191, s14, v79
	global_store_dwordx4 v238, v[76:79], s[24:25] offset:576
	s_waitcnt vmcnt(31)
	v_lshlrev_b32_e32 v252, 16, v192
	v_and_b32_e32 v192, 0xffff0000, v192
	v_lshlrev_b32_e32 v253, 16, v193
	v_and_b32_e32 v193, 0xffff0000, v193
	v_fma_f32 v80, v252, s14, v80
	v_fma_f32 v81, v192, s14, v81
	v_fma_f32 v82, v253, s14, v82
	v_fma_f32 v83, v193, s14, v83
	global_store_dwordx4 v239, v[80:83], s[24:25]
	s_waitcnt vmcnt(31)
	v_lshlrev_b32_e32 v252, 16, v194
	v_and_b32_e32 v194, 0xffff0000, v194
	v_lshlrev_b32_e32 v253, 16, v195
	v_and_b32_e32 v195, 0xffff0000, v195
	v_fma_f32 v72, v252, s14, v72
	v_fma_f32 v73, v194, s14, v73
	v_fma_f32 v74, v253, s14, v74
	v_fma_f32 v75, v195, s14, v75
	global_store_dwordx4 v239, v[72:75], s[24:25] offset:64
	s_waitcnt vmcnt(31)
	v_lshlrev_b32_e32 v252, 16, v196
	v_and_b32_e32 v196, 0xffff0000, v196
	v_lshlrev_b32_e32 v253, 16, v197
	v_and_b32_e32 v197, 0xffff0000, v197
	v_fma_f32 v68, v252, s14, v68
	v_fma_f32 v69, v196, s14, v69
	v_fma_f32 v70, v253, s14, v70
	v_fma_f32 v71, v197, s14, v71
	global_store_dwordx4 v239, v[68:71], s[24:25] offset:512
	s_waitcnt vmcnt(31)
	v_lshlrev_b32_e32 v252, 16, v198
	v_and_b32_e32 v198, 0xffff0000, v198
	v_lshlrev_b32_e32 v253, 16, v199
	v_and_b32_e32 v199, 0xffff0000, v199
	v_fma_f32 v64, v252, s14, v64
	v_fma_f32 v65, v198, s14, v65
	v_fma_f32 v66, v253, s14, v66
	v_fma_f32 v67, v199, s14, v67
	global_store_dwordx4 v239, v[64:67], s[24:25] offset:576
	s_waitcnt vmcnt(31)
	v_lshlrev_b32_e32 v252, 16, v204
	v_and_b32_e32 v204, 0xffff0000, v204
	v_lshlrev_b32_e32 v253, 16, v205
	v_and_b32_e32 v205, 0xffff0000, v205
	v_fma_f32 v60, v252, s14, v60
	v_fma_f32 v61, v204, s14, v61
	v_fma_f32 v62, v253, s14, v62
	v_fma_f32 v63, v205, s14, v63
	global_store_dwordx4 v240, v[60:63], s[24:25]
	s_waitcnt vmcnt(31)
	v_lshlrev_b32_e32 v252, 16, v206
	v_and_b32_e32 v206, 0xffff0000, v206
	v_lshlrev_b32_e32 v253, 16, v207
	v_and_b32_e32 v207, 0xffff0000, v207
	v_fma_f32 v56, v252, s14, v56
	v_fma_f32 v57, v206, s14, v57
	v_fma_f32 v58, v253, s14, v58
	v_fma_f32 v59, v207, s14, v59
	global_store_dwordx4 v240, v[56:59], s[24:25] offset:64
	s_waitcnt vmcnt(31)
	v_lshlrev_b32_e32 v252, 16, v208
	v_and_b32_e32 v208, 0xffff0000, v208
	v_lshlrev_b32_e32 v253, 16, v209
	v_and_b32_e32 v209, 0xffff0000, v209
	v_fma_f32 v52, v252, s14, v52
	v_fma_f32 v53, v208, s14, v53
	v_fma_f32 v54, v253, s14, v54
	v_fma_f32 v55, v209, s14, v55
	global_store_dwordx4 v240, v[52:55], s[24:25] offset:512
	s_waitcnt vmcnt(31)
	v_lshlrev_b32_e32 v252, 16, v210
	v_and_b32_e32 v210, 0xffff0000, v210
	v_lshlrev_b32_e32 v253, 16, v211
	v_and_b32_e32 v211, 0xffff0000, v211
	v_fma_f32 v44, v252, s14, v44
	v_fma_f32 v45, v210, s14, v45
	v_fma_f32 v46, v253, s14, v46
	v_fma_f32 v47, v211, s14, v47
	global_store_dwordx4 v240, v[44:47], s[24:25] offset:576
	s_waitcnt vmcnt(31)
	v_lshlrev_b32_e32 v252, 16, v212
	v_and_b32_e32 v212, 0xffff0000, v212
	v_lshlrev_b32_e32 v253, 16, v213
	v_and_b32_e32 v213, 0xffff0000, v213
	v_fma_f32 v48, v252, s14, v48
	v_fma_f32 v49, v212, s14, v49
	v_fma_f32 v50, v253, s14, v50
	v_fma_f32 v51, v213, s14, v51
	global_store_dwordx4 v241, v[48:51], s[24:25]
	s_waitcnt vmcnt(31)
	v_lshlrev_b32_e32 v252, 16, v214
	v_and_b32_e32 v214, 0xffff0000, v214
	v_lshlrev_b32_e32 v253, 16, v215
	v_and_b32_e32 v215, 0xffff0000, v215
	v_fma_f32 v40, v252, s14, v40
	v_fma_f32 v41, v214, s14, v41
	v_fma_f32 v42, v253, s14, v42
	v_fma_f32 v43, v215, s14, v43
	global_store_dwordx4 v241, v[40:43], s[24:25] offset:64
	s_waitcnt vmcnt(31)
	v_lshlrev_b32_e32 v252, 16, v216
	v_and_b32_e32 v216, 0xffff0000, v216
	v_lshlrev_b32_e32 v253, 16, v217
	v_and_b32_e32 v217, 0xffff0000, v217
	v_fma_f32 v36, v252, s14, v36
	v_fma_f32 v37, v216, s14, v37
	v_fma_f32 v38, v253, s14, v38
	v_fma_f32 v39, v217, s14, v39
	global_store_dwordx4 v241, v[36:39], s[24:25] offset:512
	s_waitcnt vmcnt(31)
	v_lshlrev_b32_e32 v252, 16, v218
	v_and_b32_e32 v218, 0xffff0000, v218
	v_lshlrev_b32_e32 v253, 16, v219
	v_and_b32_e32 v219, 0xffff0000, v219
	v_fma_f32 v28, v252, s14, v28
	v_fma_f32 v29, v218, s14, v29
	v_fma_f32 v30, v253, s14, v30
	v_fma_f32 v31, v219, s14, v31
	global_store_dwordx4 v241, v[28:31], s[24:25] offset:576
	s_waitcnt vmcnt(31)
	v_lshlrev_b32_e32 v252, 16, v220
	v_and_b32_e32 v220, 0xffff0000, v220
	v_lshlrev_b32_e32 v253, 16, v221
	v_and_b32_e32 v221, 0xffff0000, v221
	v_fma_f32 v32, v252, s14, v32
	v_fma_f32 v33, v220, s14, v33
	v_fma_f32 v34, v253, s14, v34
	v_fma_f32 v35, v221, s14, v35
	global_store_dwordx4 v242, v[32:35], s[24:25]
	s_waitcnt vmcnt(31)
	v_lshlrev_b32_e32 v252, 16, v222
	v_and_b32_e32 v222, 0xffff0000, v222
	v_lshlrev_b32_e32 v253, 16, v223
	v_and_b32_e32 v223, 0xffff0000, v223
	v_fma_f32 v24, v252, s14, v24
	v_fma_f32 v25, v222, s14, v25
	v_fma_f32 v26, v253, s14, v26
	v_fma_f32 v27, v223, s14, v27
	global_store_dwordx4 v242, v[24:27], s[24:25] offset:64
	s_waitcnt vmcnt(31)
	v_lshlrev_b32_e32 v252, 16, v224
	v_and_b32_e32 v224, 0xffff0000, v224
	v_lshlrev_b32_e32 v253, 16, v225
	v_and_b32_e32 v225, 0xffff0000, v225
	v_fma_f32 v20, v252, s14, v20
	v_fma_f32 v21, v224, s14, v21
	v_fma_f32 v22, v253, s14, v22
	v_fma_f32 v23, v225, s14, v23
	global_store_dwordx4 v242, v[20:23], s[24:25] offset:512
	s_waitcnt vmcnt(31)
	v_lshlrev_b32_e32 v252, 16, v226
	v_and_b32_e32 v226, 0xffff0000, v226
	v_lshlrev_b32_e32 v253, 16, v227
	v_and_b32_e32 v227, 0xffff0000, v227
	v_fma_f32 v12, v252, s14, v12
	v_fma_f32 v13, v226, s14, v13
	v_fma_f32 v14, v253, s14, v14
	v_fma_f32 v15, v227, s14, v15
	global_store_dwordx4 v242, v[12:15], s[24:25] offset:576
	s_waitcnt vmcnt(31)
	v_lshlrev_b32_e32 v252, 16, v228
	v_and_b32_e32 v228, 0xffff0000, v228
	v_lshlrev_b32_e32 v253, 16, v229
	v_and_b32_e32 v229, 0xffff0000, v229
	v_fma_f32 v16, v252, s14, v16
	v_fma_f32 v17, v228, s14, v17
	v_fma_f32 v18, v253, s14, v18
	v_fma_f32 v19, v229, s14, v19
	global_store_dwordx4 v243, v[16:19], s[24:25]
	s_waitcnt vmcnt(31)
	v_lshlrev_b32_e32 v252, 16, v230
	v_and_b32_e32 v230, 0xffff0000, v230
	v_lshlrev_b32_e32 v253, 16, v231
	v_and_b32_e32 v231, 0xffff0000, v231
	v_fma_f32 v8, v252, s14, v8
	v_fma_f32 v9, v230, s14, v9
	v_fma_f32 v10, v253, s14, v10
	v_fma_f32 v11, v231, s14, v11
	global_store_dwordx4 v243, v[8:11], s[24:25] offset:64
	s_waitcnt vmcnt(31)
	v_lshlrev_b32_e32 v252, 16, v232
	v_and_b32_e32 v232, 0xffff0000, v232
	v_lshlrev_b32_e32 v253, 16, v233
	v_and_b32_e32 v233, 0xffff0000, v233
	v_fma_f32 v4, v252, s14, v4
	v_fma_f32 v5, v232, s14, v5
	v_fma_f32 v6, v253, s14, v6
	v_fma_f32 v7, v233, s14, v7
	global_store_dwordx4 v243, v[4:7], s[24:25] offset:512
	s_waitcnt vmcnt(31)
	v_lshlrev_b32_e32 v252, 16, v234
	v_and_b32_e32 v234, 0xffff0000, v234
	v_lshlrev_b32_e32 v253, 16, v235
	v_and_b32_e32 v235, 0xffff0000, v235
	v_fma_f32 v0, v252, s14, v0
	v_fma_f32 v1, v234, s14, v1
	v_fma_f32 v2, v253, s14, v2
	v_fma_f32 v3, v235, s14, v3
	global_store_dwordx4 v243, v[0:3], s[24:25] offset:576
	s_cbranch_vccnz .LBB0_1696
	s_andn2_b64 vcc, exec, s[6:7]
	s_cbranch_vccnz .LBB0_1695
	s_barrier
	s_branch .LBB0_1695
